# longer sleep between polls in the two remaining cg-style grid syncs (less contention on the counter)
# baseline (speedup 1.0000x reference)
; __global__ void __launch_bounds__(512, 2) mega(P p_arg) {
;     ...
;         if (code & 128) { if (si + 1 < nseq) cg::this_grid().sync(); }
;         else __syncthreads();
.LBB0_987:
	s_sleep 20
	global_load_dword v2, v1, s[2:3] offset:32 sc1
	s_waitcnt vmcnt(0)
	v_and_b32_e32 v2, 0xffff0000, v2
	v_cmp_ne_u32_e32 vcc, v2, v0
	s_or_b64 s[4:5], vcc, s[4:5]
	s_andn2_b64 exec, exec, s[4:5]
	s_cbranch_execnz .LBB0_987
